# m2_c tail (state/diagonal MFMAs, gating, RMS norm) rewritten: all global operands issued at the start of the scores segment, per-ph straight-line paths, LDS reads one iteration ahead
# baseline (speedup 1.0000x reference)
; __device__ __forceinline__ u32x2 pack4(const f32x4 a) { u32x2 v; v.x = cvt_pk_bf16(a[0], a[1]); v.y = cvt_pk_bf16(a[2], a[3]); return v; }
; #define LBAR() do { asm volatile("s_waitcnt lgkmcnt(0)" ::: "memory"); __builtin_amdgcn_s_barrier(); asm volatile("" ::: "memory"); } while (0)
; __device__ void m2_c_unit(LAS unsigned char* lds, KP& P_, int l, int bc, int grp) {
;     ...
;     LBAR();
;     { const float rinv = __builtin_amdgcn_rsqf((ss[tq * 2] + ss[tq * 2 + 1]) * (1.0f / 192.0f) + RMS_EPS);
;       bf16_t* mixed = (bf16_t*)(p.ws + WS_MIXED); const float* nw = p.in[10] + l * 384 + grp * 192;
; #pragma unroll
;       for (int i = 0; i < 6; ++i) { const int pch = (ph * 6 + i) * 16 + fq * 4; f32x4 r;
; #pragma unroll
;           for (int j = 0; j < 4; ++j) r[j] = yv[i][j] * rinv * nwv[i][j];
;           *(u32x2*)(mixed + orow * DM + 384 + grp * 192 + pch) = pack4(r); } }
;     LBAR();
.LBB0_303:
	s_or_b64 exec, exec, s[6:7]
	s_branch .LBB0_307
.Lm2ct_done:
	s_waitcnt lgkmcnt(0)
	s_barrier
.LBB0_305:
	s_mov_b64 s[6:7], 0

; #define LAS __attribute__((address_space(3)))
; __device__ void m2_c_unit(LAS unsigned char* lds, KP& P_, int l, int bc, int grp) {
;     ...
;     {
;         const int tt = wid >> 1;
; #pragma unroll
;         for (int qq = 0; qq < 2; ++qq) { const int st = (wid & 1) * 2 + qq; f32x4 acc = (f32x4){0.f, 0.f, 0.f, 0.f};
;             if (st <= tt) {
; #pragma unroll
;                 for (int ks = 0; ks < 4; ++ks) { const bf16x8 a = *(const LAS bf16x8*)(BM + (st * 16 + fr) * 136 + ks * 32 + fq * 8), b = *(const LAS bf16x8*)(CM + (tt * 16 + fr) * 136 + ks * 32 + fq * 8); acc = MFMA16(a, b, acc); } }
;             const int tq = tt * 16 + fr;
; #pragma unroll
;             for (int hh = 0; hh < 3; ++hh) { f32x4 r; const float at = acs[hh * 64 + tq];
; #pragma unroll
;                 for (int j = 0; j < 4; ++j) { const int s = st * 16 + fq * 4 + j; r[j] = (s <= tq) ? acc[j] * __expf(at - acs[hh * 64 + s]) * dtl[hh * 64 + s] : 0.f; }
;                 *(LAS u32x2*)(PH + hh * 4608 + tq * 72 + st * 16 + fq * 4) = pack4(r); } }
;     }
;     LBAR();
;     const int tt = wid & 3, ph = wid >> 2, tq = tt * 16 + fr; const size_t orow = (size_t)bc * 64 + tq;
;     const unsigned xn_base = (unsigned)(size_t)XN;
;     f32x4 yv[6], nwv[6];
; #pragma unroll
;     for (int i = 0; i < 6; ++i) nwv[i] = *(const f32x4*)(p.in[10] + l * 384 + grp * 192 + (ph * 6 + i) * 16 + fq * 4);
;     { bf16x8 cf[4];
; #pragma unroll
;       for (int ks = 0; ks < 4; ++ks) cf[ks] = *(const LAS bf16x8*)(CM + tq * 136 + ks * 32 + fq * 8);
;       const bf16_t* stm = (const bf16_t*)(p.ws + WS_STM); float ssq = 0.f;
;       u32x2 zraw[6];
; #pragma unroll
;       for (int i = 0; i < 6; ++i) zraw[i] = *(const u32x2*)(proj + orow * NPROJ + C_Z + grp * 192 + (ph * 6 + i) * 16 + fq * 4);
;       bf16x8 hf[4];
; #pragma unroll
;       for (int ks = 0; ks < 4; ++ks) hf[ks] = *(const bf16x8*)(stm + (((size_t)bc * 6 + grp * 3 + ((ph * 6) >> 2)) * 64 + ((ph * 6) & 3) * 16 + fr) * 128 + ks * 32 + fq * 8);
; #pragma unroll
;       for (int i = 0; i < 6; ++i) { const int pt = ph * 6 + i, hh = pt >> 2, head = grp * 3 + hh;
;           f32x4 ad = (f32x4){0.f, 0.f, 0.f, 0.f}, ao = (f32x4){0.f, 0.f, 0.f, 0.f};
;           bf16x8 hc[4];
; #pragma unroll
;           for (int ks = 0; ks < 4; ++ks) hc[ks] = hf[ks];
;           if (i < 5) { const int pn = pt + 1;
; #pragma unroll
.LBB0_423:
	s_andn2_saveexec_b64 s[14:15], s[14:15]
	s_movk_i32 s12, 0x190
	v_mul_lo_u32 v0, v3, s12
	v_lshlrev_b32_e32 v3, 1, v121
	v_add3_u32 v0, 0, v0, v3
	ds_write_b128 v0, v[8:11]
	s_or_b64 exec, exec, s[14:15]
	v_ashrrev_i32_e32 v0, 6, v2
	v_and_b32_e32 v142, 15, v2
	v_ashrrev_i32_e32 v16, 7, v2
	v_lshlrev_b32_e32 v3, 1, v0
	v_lshl_or_b32 v13, v16, 4, v142
	v_bfe_u32 v141, v2, 4, 2
	s_waitcnt lgkmcnt(0)
	s_barrier
	v_and_b32_e32 v143, 15, v198
	v_bfe_u32 v144, v198, 4, 2
	v_bfe_u32 v146, v198, 6, 2
	v_lshrrev_b32_e32 v156, 8, v198
	v_lshl_add_u32 v158, v146, 4, v143
	s_load_dwordx4 s[72:75], s[24:25], 0x48
	s_mul_i32 s62, s96, 6
	s_mul_i32 s63, s22, 3
	s_add_i32 s62, s62, s63
	s_mul_i32 s64, s13, 6
	s_add_i32 s64, s64, s63
	s_lshl_b32 s65, s62, 14
	v_mul_u32_u24_e32 v210, 0x6000, v156
	v_lshl_add_u32 v210, v143, 8, v210
	v_lshl_add_u32 v210, v144, 4, v210
	v_add_u32_e32 v210, s65, v210
	v_mov_b32_e32 v211, 0
	s_add_u32 s66, s6, 0xcf30000
	s_addc_u32 s67, s7, 0
	v_lshl_add_u64 v[210:211], s[66:67], 0, v[210:211]
	s_mov_b64 s[68:69], 0x1000
	global_load_dwordx4 v[36:39], v[210:211], off
	global_load_dwordx4 v[40:43], v[210:211], off offset:64
	global_load_dwordx4 v[44:47], v[210:211], off offset:128
	global_load_dwordx4 v[48:51], v[210:211], off offset:192
	v_lshl_add_u64 v[210:211], v[210:211], 0, s[68:69]
	global_load_dwordx4 v[52:55], v[210:211], off
	global_load_dwordx4 v[56:59], v[210:211], off offset:64
	global_load_dwordx4 v[60:63], v[210:211], off offset:128
	global_load_dwordx4 v[64:67], v[210:211], off offset:192
	v_lshl_add_u64 v[210:211], v[210:211], 0, s[68:69]
	global_load_dwordx4 v[68:71], v[210:211], off
	global_load_dwordx4 v[72:75], v[210:211], off offset:64
	global_load_dwordx4 v[76:79], v[210:211], off offset:128
	global_load_dwordx4 v[80:83], v[210:211], off offset:192
	v_lshl_add_u64 v[210:211], v[210:211], 0, s[68:69]
	global_load_dwordx4 v[84:87], v[210:211], off
	global_load_dwordx4 v[88:91], v[210:211], off offset:64
	global_load_dwordx4 v[92:95], v[210:211], off offset:128
	global_load_dwordx4 v[96:99], v[210:211], off offset:192
	v_lshl_add_u64 v[210:211], v[210:211], 0, s[68:69]
	global_load_dwordx4 v[100:103], v[210:211], off
	global_load_dwordx4 v[108:111], v[210:211], off offset:64
	global_load_dwordx4 v[112:115], v[210:211], off offset:128
	global_load_dwordx4 v[116:119], v[210:211], off offset:192
	v_lshl_add_u64 v[210:211], v[210:211], 0, s[68:69]
	global_load_dwordx4 v[120:123], v[210:211], off
	global_load_dwordx4 v[124:127], v[210:211], off offset:64
	global_load_dwordx4 v[128:131], v[210:211], off offset:128
	global_load_dwordx4 v[132:135], v[210:211], off offset:192
	s_lshl_b32 s65, s96, 6
	v_add_u32_e32 v216, s65, v158
	v_mul_u32_u24_e32 v216, 0x1800, v216
	s_mul_i32 s65, s22, 0x180
	v_add_u32_e32 v216, s65, v216
	v_mul_u32_u24_e32 v217, 0xc0, v156
	v_add_u32_e32 v216, v216, v217
	v_lshl_add_u32 v216, v144, 3, v216
	v_mov_b32_e32 v217, 0
	v_lshl_add_u64 v[216:217], s[6:7], 0, v[216:217]
	global_load_dwordx2 v[148:149], v[216:217], off offset:3072
	global_load_dwordx2 v[150:151], v[216:217], off offset:3104
	global_load_dwordx2 v[152:153], v[216:217], off offset:3136
	global_load_dwordx2 v[154:155], v[216:217], off offset:3168
	global_load_dwordx2 v[160:161], v[216:217], off offset:3200
	global_load_dwordx2 v[162:163], v[216:217], off offset:3232
	s_mul_i32 s65, s13, 0x600
	s_mul_i32 s66, s22, 0x300
	s_add_i32 s65, s65, s66
	v_mul_u32_u24_e32 v174, 0x180, v156
	v_lshl_add_u32 v174, v144, 4, v174
	v_add_u32_e32 v174, s65, v174
	v_mov_b32_e32 v175, 0
	s_lshl_b32 s64, s64, 2
	s_waitcnt lgkmcnt(0)
	v_lshl_add_u64 v[174:175], s[74:75], 0, v[174:175]
	global_load_dwordx4 v[164:167], v[174:175], off
	global_load_dwordx4 v[184:187], v[174:175], off offset:64
	global_load_dwordx4 v[188:191], v[174:175], off offset:128
	global_load_dwordx4 v[222:225], v[174:175], off offset:192
	global_load_dwordx4 v[226:229], v[174:175], off offset:256
	global_load_dwordx4 v[230:233], v[174:175], off offset:320
	s_add_u32 s66, s72, s64
	s_addc_u32 s67, s73, 0
	s_load_dword s76, s[66:67], 0x0
	s_load_dword s78, s[66:67], 0x4
	s_load_dword s70, s[66:67], 0x8
	v_and_b32_e32 v17, 2, v3
	v_mul_lo_u32 v3, v13, s10
	v_add_u32_e32 v18, 0, v3
	v_lshlrev_b32_e32 v32, 4, v141
	v_lshlrev_b32_e32 v3, 7, v13
	v_add_u32_e32 v15, 0, v32
	v_add3_u32 v14, v18, v3, v32
	v_cmp_le_i32_e32 vcc, v17, v16
	v_lshlrev_b32_e32 v19, 4, v17
	v_mov_b32_e32 v20, 0
	v_mov_b32_e32 v8, 0
	v_mov_b32_e32 v9, 0
	v_mov_b32_e32 v10, 0
	v_mov_b32_e32 v11, 0
	s_and_saveexec_b64 s[42:43], vcc
	s_cbranch_execz .LBB0_427
	v_or_b32_e32 v3, v19, v142
	s_movk_i32 s12, 0x110
	v_mad_u32_u24 v3, v3, s12, v15
	ds_read_b128 v[8:11], v3 offset:27648
	ds_read_b128 v[22:25], v14 offset:45056
	s_waitcnt lgkmcnt(0)
	v_mfma_f32_16x16x32_bf16 v[8:11], v[8:11], v[22:25], 0
	ds_read_b128 v[22:25], v3 offset:27712
	ds_read_b128 v[26:29], v14 offset:45120
	s_waitcnt lgkmcnt(0)
	v_mfma_f32_16x16x32_bf16 v[8:11], v[22:25], v[26:29], v[8:11]
	ds_read_b128 v[22:25], v3 offset:27776
	ds_read_b128 v[26:29], v14 offset:45184
	s_waitcnt lgkmcnt(0)
	v_mfma_f32_16x16x32_bf16 v[8:11], v[22:25], v[26:29], v[8:11]
	ds_read_b128 v[22:25], v3 offset:27840
	ds_read_b128 v[26:29], v14 offset:45248
	s_waitcnt lgkmcnt(0)
	v_mfma_f32_16x16x32_bf16 v[8:11], v[22:25], v[26:29], v[8:11]

; #define LAS __attribute__((address_space(3)))
; __device__ void m2_c_unit(LAS unsigned char* lds, KP& P_, int l, int bc, int grp) {
;     ...
;                 *(LAS u32x2*)(PH + hh * 4608 + tq * 72 + st * 16 + fq * 4) = pack4(r); } }
;     }
;     LBAR();
;     const int tt = wid & 3, ph = wid >> 2, tq = tt * 16 + fr; const size_t orow = (size_t)bc * 64 + tq;
;     const unsigned xn_base = (unsigned)(size_t)XN;
;     f32x4 yv[6], nwv[6];
; #pragma unroll
;     for (int i = 0; i < 6; ++i) nwv[i] = *(const f32x4*)(p.in[10] + l * 384 + grp * 192 + (ph * 6 + i) * 16 + fq * 4);
;     { bf16x8 cf[4];
; #pragma unroll
;       for (int ks = 0; ks < 4; ++ks) cf[ks] = *(const LAS bf16x8*)(CM + tq * 136 + ks * 32 + fq * 8);
;       const bf16_t* stm = (const bf16_t*)(p.ws + WS_STM); float ssq = 0.f;
;       u32x2 zraw[6];
; #pragma unroll
;       for (int i = 0; i < 6; ++i) zraw[i] = *(const u32x2*)(proj + orow * NPROJ + C_Z + grp * 192 + (ph * 6 + i) * 16 + fq * 4);
;       bf16x8 hf[4];
; #pragma unroll
;       for (int ks = 0; ks < 4; ++ks) hf[ks] = *(const bf16x8*)(stm + (((size_t)bc * 6 + grp * 3 + ((ph * 6) >> 2)) * 64 + ((ph * 6) & 3) * 16 + fr) * 128 + ks * 32 + fq * 8);
; #pragma unroll
;       for (int i = 0; i < 6; ++i) { const int pt = ph * 6 + i, hh = pt >> 2, head = grp * 3 + hh;
;           f32x4 ad = (f32x4){0.f, 0.f, 0.f, 0.f}, ao = (f32x4){0.f, 0.f, 0.f, 0.f};
;           bf16x8 hc[4];
; #pragma unroll
;           for (int ks = 0; ks < 4; ++ks) hc[ks] = hf[ks];
;           if (i < 5) { const int pn = pt + 1;
; #pragma unroll
;               for (int ks = 0; ks < 4; ++ks) hf[ks] = *(const bf16x8*)(stm + (((size_t)bc * 6 + grp * 3 + (pn >> 2)) * 64 + (pn & 3) * 16 + fr) * 128 + ks * 32 + fq * 8); }
; #pragma unroll
;           for (int ks = 0; ks < 2; ++ks) { const unsigned ta = xn_base + (unsigned)((32 * ks + 8 * fq + (fr >> 2)) * 400 + (16 * pt + 4 * (fr & 3)) * 2);
;               const bf16x8 a = tr_frag(ta, ta + 1600u), b = *(const LAS bf16x8*)(PH + hh * 4608 + tq * 72 + ks * 32 + fq * 8); ad = MFMA16(a, b, ad); }
; #pragma unroll
;           for (int ks = 0; ks < 4; ++ks) ao = MFMA16(hc[ks], cf[ks], ao);
;           const float ea = __expf(acs[hh * 64 + tq]), dsk = p.in[9][l * 6 + head]; const int pch = pt * 16 + fq * 4;
;           const float zv[4] = {bflo(zraw[i].x), bfhi(zraw[i].x), bflo(zraw[i].y), bfhi(zraw[i].y)};
;           f32x4 y;
.LBB0_477:
	s_or_b64 exec, exec, s[14:15]
	v_cvt_pk_bf16_f32 v10, v16, v15
	v_cvt_pk_bf16_f32 v11, v9, v8
	ds_write_b64 v13, v[10:11] offset:18432
	s_waitcnt lgkmcnt(0)
	s_barrier
	v_mul_u32_u24_e32 v196, 0x110, v158
	v_lshl_add_u32 v196, v144, 4, v196
	v_mul_u32_u24_e32 v180, 0x90, v158
	v_lshl_add_u32 v180, v144, 4, v180
	v_add_u32_e32 v180, 0xf400, v180
	v_lshlrev_b32_e32 v192, 2, v158
	v_add_u32_e32 v192, 0x16300, v192
	v_mul_u32_u24_e32 v182, 0x190, v158
	v_lshl_add_u32 v182, v144, 3, v182
	v_lshrrev_b32_e32 v179, 2, v143
	v_lshl_add_u32 v179, v144, 3, v179
	v_mul_u32_u24_e32 v179, 0x190, v179
	v_and_b32_e32 v194, 3, v143
	v_lshl_add_u32 v179, v194, 3, v179
	v_lshl_add_u32 v194, v158, 1, v156
	v_lshlrev_b32_e32 v194, 2, v194
	v_add_u32_e32 v194, 0x16900, v194
	v_and_b32_e32 v170, 63, v198
	v_xor_b32_e32 v172, 32, v170
	v_xor_b32_e32 v170, 16, v170
	v_lshlrev_b32_e32 v170, 2, v170
	v_lshlrev_b32_e32 v172, 2, v172
	v_mov_b32_e32 v176, 0
	v_lshlrev_b32_e32 v210, 11, v158
	v_mul_u32_u24_e32 v211, 0xc0, v156
	v_add_u32_e32 v210, v210, v211
	v_lshl_add_u32 v210, v144, 3, v210
	s_lshl_b32 s65, s96, 17
	s_mul_i32 s66, s22, 0x180
	s_add_i32 s65, s65, s66
	v_add_u32_e32 v210, s65, v210
	v_mov_b32_e32 v211, 0
	s_add_u32 s66, s6, 0x6180300
	s_addc_u32 s67, s7, 0
	v_lshl_add_u64 v[210:211], s[66:67], 0, v[210:211]
	v_readfirstlane_b32 s62, v156
	ds_read_b128 v[8:11], v196 offset:45056
	ds_read_b128 v[12:15], v196 offset:45120
	ds_read_b128 v[16:19], v196 offset:45184
	ds_read_b128 v[20:23], v196 offset:45248
	s_cmp_eq_u32 s62, 0
	s_cbranch_scc0 .Lm2ct_ph1
	ds_read_b128 v[24:27], v180 offset:0
	ds_read_b128 v[28:31], v180 offset:64
	ds_read_b128 v[32:35], v180 offset:9216
	ds_read_b128 v[104:107], v180 offset:9280
	ds_read_b32 v2, v192 offset:0
	ds_read_b32 v0, v192 offset:256
	ds_read_b64_tr_b16 v[236:237], v179 offset:0
	ds_read_b64_tr_b16 v[238:239], v179 offset:1600
	ds_read_b64_tr_b16 v[240:241], v179 offset:12800
	ds_read_b64_tr_b16 v[242:243], v179 offset:14400
	ds_read_b64 v[234:235], v182 offset:0
	s_waitcnt vmcnt(0) lgkmcnt(0)
	v_mul_f32_e32 v2, 0x3fb8aa3b, v2
	v_mul_f32_e32 v0, 0x3fb8aa3b, v0
	v_exp_f32_e32 v2, v2
	v_exp_f32_e32 v0, v0
	ds_read_b64_tr_b16 v[244:245], v179 offset:32
	ds_read_b64_tr_b16 v[246:247], v179 offset:1632
	ds_read_b64_tr_b16 v[248:249], v179 offset:12832
	ds_read_b64_tr_b16 v[250:251], v179 offset:14432
	ds_read_b64 v[168:169], v182 offset:32
	s_waitcnt lgkmcnt(5)
	v_mfma_f32_16x16x32_bf16 v[36:39], v[36:39], v[8:11], 0
	v_mfma_f32_16x16x32_bf16 v[36:39], v[40:43], v[12:15], v[36:39]
	v_mfma_f32_16x16x32_bf16 v[36:39], v[44:47], v[16:19], v[36:39]
	v_mfma_f32_16x16x32_bf16 v[36:39], v[48:51], v[20:23], v[36:39]
	v_mfma_f32_16x16x32_bf16 v[40:43], v[236:239], v[24:27], 0
	v_mfma_f32_16x16x32_bf16 v[40:43], v[240:243], v[28:31], v[40:43]
	v_lshlrev_b32_e32 v44, 16, v148
	v_and_b32_e32 v45, 0xffff0000, v148
	v_lshlrev_b32_e32 v46, 16, v149
	v_and_b32_e32 v47, 0xffff0000, v149
	v_mul_f32_e32 v48, 0xbfb8aa3b, v44
	v_mul_f32_e32 v49, 0xbfb8aa3b, v45
	v_mul_f32_e32 v50, 0xbfb8aa3b, v46
	v_mul_f32_e32 v51, 0xbfb8aa3b, v47
	v_exp_f32_e32 v48, v48
	v_exp_f32_e32 v49, v49
	v_exp_f32_e32 v50, v50
	v_exp_f32_e32 v51, v51
	v_add_f32_e32 v48, 1.0, v48
	v_add_f32_e32 v49, 1.0, v49
	v_add_f32_e32 v50, 1.0, v50
	v_add_f32_e32 v51, 1.0, v51
	v_rcp_f32_e32 v48, v48
	v_rcp_f32_e32 v49, v49
	v_rcp_f32_e32 v50, v50
	v_rcp_f32_e32 v51, v51
	s_nop 0
	v_pk_mul_f32 v[48:49], v[48:49], v[44:45]
	v_pk_mul_f32 v[50:51], v[50:51], v[46:47]
	v_pk_fma_f32 v[36:37], v[36:37], v[2:3], v[40:41] op_sel_hi:[1,0,1]
	v_pk_fma_f32 v[38:39], v[38:39], v[2:3], v[42:43] op_sel_hi:[1,0,1]
	v_lshlrev_b32_e32 v40, 16, v234
	v_and_b32_e32 v41, 0xffff0000, v234
	v_lshlrev_b32_e32 v42, 16, v235
	v_and_b32_e32 v43, 0xffff0000, v235
	v_pk_fma_f32 v[36:37], s[76:77], v[40:41], v[36:37] op_sel_hi:[0,1,1]
	v_pk_fma_f32 v[38:39], s[76:77], v[42:43], v[38:39] op_sel_hi:[0,1,1]
	v_pk_mul_f32 v[36:37], v[48:49], v[36:37]
	v_pk_mul_f32 v[38:39], v[50:51], v[38:39]
	v_fmac_f32_e32 v176, v36, v36
	v_fmac_f32_e32 v176, v37, v37
	v_fmac_f32_e32 v176, v38, v38
	v_fmac_f32_e32 v176, v39, v39
	ds_read_b64_tr_b16 v[236:237], v179 offset:64
	ds_read_b64_tr_b16 v[238:239], v179 offset:1664
	ds_read_b64_tr_b16 v[240:241], v179 offset:12864
	ds_read_b64_tr_b16 v[242:243], v179 offset:14464
	ds_read_b64 v[234:235], v182 offset:64
	s_waitcnt lgkmcnt(5)
	v_mfma_f32_16x16x32_bf16 v[52:55], v[52:55], v[8:11], 0
	v_mfma_f32_16x16x32_bf16 v[52:55], v[56:59], v[12:15], v[52:55]
	v_mfma_f32_16x16x32_bf16 v[52:55], v[60:63], v[16:19], v[52:55]
	v_mfma_f32_16x16x32_bf16 v[52:55], v[64:67], v[20:23], v[52:55]
	v_mfma_f32_16x16x32_bf16 v[56:59], v[244:247], v[24:27], 0
	v_mfma_f32_16x16x32_bf16 v[56:59], v[248:251], v[28:31], v[56:59]
	v_lshlrev_b32_e32 v60, 16, v150
	v_and_b32_e32 v61, 0xffff0000, v150
	v_lshlrev_b32_e32 v62, 16, v151
	v_and_b32_e32 v63, 0xffff0000, v151
	v_mul_f32_e32 v64, 0xbfb8aa3b, v60
	v_mul_f32_e32 v65, 0xbfb8aa3b, v61
	v_mul_f32_e32 v66, 0xbfb8aa3b, v62
	v_mul_f32_e32 v67, 0xbfb8aa3b, v63
	v_exp_f32_e32 v64, v64
	v_exp_f32_e32 v65, v65
	v_exp_f32_e32 v66, v66
	v_exp_f32_e32 v67, v67
	v_add_f32_e32 v64, 1.0, v64
	v_add_f32_e32 v65, 1.0, v65
	v_add_f32_e32 v66, 1.0, v66
	v_add_f32_e32 v67, 1.0, v67
	v_rcp_f32_e32 v64, v64
	v_rcp_f32_e32 v65, v65
	v_rcp_f32_e32 v66, v66
	v_rcp_f32_e32 v67, v67
	s_nop 0
	v_pk_mul_f32 v[64:65], v[64:65], v[60:61]
	v_pk_mul_f32 v[66:67], v[66:67], v[62:63]
	v_pk_fma_f32 v[52:53], v[52:53], v[2:3], v[56:57] op_sel_hi:[1,0,1]
	v_pk_fma_f32 v[54:55], v[54:55], v[2:3], v[58:59] op_sel_hi:[1,0,1]
	v_lshlrev_b32_e32 v56, 16, v168
	v_and_b32_e32 v57, 0xffff0000, v168
	v_lshlrev_b32_e32 v58, 16, v169
	v_and_b32_e32 v59, 0xffff0000, v169
	v_pk_fma_f32 v[52:53], s[76:77], v[56:57], v[52:53] op_sel_hi:[0,1,1]
	v_pk_fma_f32 v[54:55], s[76:77], v[58:59], v[54:55] op_sel_hi:[0,1,1]
	v_pk_mul_f32 v[52:53], v[64:65], v[52:53]
	v_pk_mul_f32 v[54:55], v[66:67], v[54:55]
	v_fmac_f32_e32 v176, v52, v52
	v_fmac_f32_e32 v176, v53, v53
	v_fmac_f32_e32 v176, v54, v54
	v_fmac_f32_e32 v176, v55, v55
	ds_read_b64_tr_b16 v[244:245], v179 offset:96
	ds_read_b64_tr_b16 v[246:247], v179 offset:1696
	ds_read_b64_tr_b16 v[248:249], v179 offset:12896
	ds_read_b64_tr_b16 v[250:251], v179 offset:14496
	ds_read_b64 v[168:169], v182 offset:96
	s_waitcnt lgkmcnt(5)
; #define LAS __attribute__((address_space(3)))
; __device__ __forceinline__ float bflo(unsigned w) { return __uint_as_float(w << 16); }
; __device__ __forceinline__ float bfhi(unsigned w) { return __uint_as_float(w & 0xffff0000u); }
; __device__ __forceinline__ float siluf_(float x) { return x * __builtin_amdgcn_rcpf(1.0f + __expf(-x)); }
; #define MFMA16(a, b, c) __builtin_amdgcn_mfma_f32_16x16x32_bf16((a), (b), (c), 0, 0, 0)
; __device__ void m2_c_unit(LAS unsigned char* lds, KP& P_, int l, int bc, int grp) {
;     ...
;       for (int i = 0; i < 6; ++i) { const int pt = ph * 6 + i, hh = pt >> 2, head = grp * 3 + hh;
;           f32x4 ad = (f32x4){0.f, 0.f, 0.f, 0.f}, ao = (f32x4){0.f, 0.f, 0.f, 0.f};
;           bf16x8 hc[4];
; #pragma unroll
;           for (int ks = 0; ks < 4; ++ks) hc[ks] = hf[ks];
;           if (i < 5) { const int pn = pt + 1;
; #pragma unroll
;               for (int ks = 0; ks < 4; ++ks) hf[ks] = *(const bf16x8*)(stm + (((size_t)bc * 6 + grp * 3 + (pn >> 2)) * 64 + (pn & 3) * 16 + fr) * 128 + ks * 32 + fq * 8); }
; #pragma unroll
;           for (int ks = 0; ks < 2; ++ks) { const unsigned ta = xn_base + (unsigned)((32 * ks + 8 * fq + (fr >> 2)) * 400 + (16 * pt + 4 * (fr & 3)) * 2);
;               const bf16x8 a = tr_frag(ta, ta + 1600u), b = *(const LAS bf16x8*)(PH + hh * 4608 + tq * 72 + ks * 32 + fq * 8); ad = MFMA16(a, b, ad); }
; #pragma unroll
;           for (int ks = 0; ks < 4; ++ks) ao = MFMA16(hc[ks], cf[ks], ao);
;           const float ea = __expf(acs[hh * 64 + tq]), dsk = p.in[9][l * 6 + head]; const int pch = pt * 16 + fq * 4;
;           const float zv[4] = {bflo(zraw[i].x), bfhi(zraw[i].x), bflo(zraw[i].y), bfhi(zraw[i].y)};
;           f32x4 y;
;           const u32x2 xraw = *(const LAS u32x2*)(XN + tq * 200 + pch); const float xsv[4] = {bflo(xraw.x), bfhi(xraw.x), bflo(xraw.y), bfhi(xraw.y)};
; #pragma unroll
;           for (int j = 0; j < 4; ++j) { y[j] = (ad[j] + ea * ao[j] + dsk * xsv[j]) * siluf_(zv[j]); ssq += y[j] * y[j]; }
;           yv[i] = y; }
	v_mfma_f32_16x16x32_bf16 v[68:71], v[68:71], v[8:11], 0
	v_mfma_f32_16x16x32_bf16 v[68:71], v[72:75], v[12:15], v[68:71]
	v_mfma_f32_16x16x32_bf16 v[68:71], v[76:79], v[16:19], v[68:71]
	v_mfma_f32_16x16x32_bf16 v[68:71], v[80:83], v[20:23], v[68:71]
	v_mfma_f32_16x16x32_bf16 v[72:75], v[236:239], v[24:27], 0
	v_mfma_f32_16x16x32_bf16 v[72:75], v[240:243], v[28:31], v[72:75]
	v_lshlrev_b32_e32 v76, 16, v152
	v_and_b32_e32 v77, 0xffff0000, v152
	v_lshlrev_b32_e32 v78, 16, v153
	v_and_b32_e32 v79, 0xffff0000, v153
	v_mul_f32_e32 v80, 0xbfb8aa3b, v76
	v_mul_f32_e32 v81, 0xbfb8aa3b, v77
	v_mul_f32_e32 v82, 0xbfb8aa3b, v78
	v_mul_f32_e32 v83, 0xbfb8aa3b, v79
	v_exp_f32_e32 v80, v80
	v_exp_f32_e32 v81, v81
	v_exp_f32_e32 v82, v82
	v_exp_f32_e32 v83, v83
	v_add_f32_e32 v80, 1.0, v80
	v_add_f32_e32 v81, 1.0, v81
	v_add_f32_e32 v82, 1.0, v82
	v_add_f32_e32 v83, 1.0, v83
	v_rcp_f32_e32 v80, v80
	v_rcp_f32_e32 v81, v81
	v_rcp_f32_e32 v82, v82
	v_rcp_f32_e32 v83, v83
	s_nop 0
	v_pk_mul_f32 v[80:81], v[80:81], v[76:77]
	v_pk_mul_f32 v[82:83], v[82:83], v[78:79]
	v_pk_fma_f32 v[68:69], v[68:69], v[2:3], v[72:73] op_sel_hi:[1,0,1]
	v_pk_fma_f32 v[70:71], v[70:71], v[2:3], v[74:75] op_sel_hi:[1,0,1]
	v_lshlrev_b32_e32 v72, 16, v234
	v_and_b32_e32 v73, 0xffff0000, v234
	v_lshlrev_b32_e32 v74, 16, v235
	v_and_b32_e32 v75, 0xffff0000, v235
	v_pk_fma_f32 v[68:69], s[76:77], v[72:73], v[68:69] op_sel_hi:[0,1,1]
	v_pk_fma_f32 v[70:71], s[76:77], v[74:75], v[70:71] op_sel_hi:[0,1,1]
	v_pk_mul_f32 v[68:69], v[80:81], v[68:69]
	v_pk_mul_f32 v[70:71], v[82:83], v[70:71]
	v_fmac_f32_e32 v176, v68, v68
	v_fmac_f32_e32 v176, v69, v69
	v_fmac_f32_e32 v176, v70, v70
	v_fmac_f32_e32 v176, v71, v71
	ds_read_b64_tr_b16 v[236:237], v179 offset:128
	ds_read_b64_tr_b16 v[238:239], v179 offset:1728
	ds_read_b64_tr_b16 v[240:241], v179 offset:12928
	ds_read_b64_tr_b16 v[242:243], v179 offset:14528
	ds_read_b64 v[234:235], v182 offset:128
	s_waitcnt lgkmcnt(5)
	v_mfma_f32_16x16x32_bf16 v[84:87], v[84:87], v[8:11], 0
	v_mfma_f32_16x16x32_bf16 v[84:87], v[88:91], v[12:15], v[84:87]
	v_mfma_f32_16x16x32_bf16 v[84:87], v[92:95], v[16:19], v[84:87]
	v_mfma_f32_16x16x32_bf16 v[84:87], v[96:99], v[20:23], v[84:87]
	v_mfma_f32_16x16x32_bf16 v[88:91], v[244:247], v[24:27], 0
	v_mfma_f32_16x16x32_bf16 v[88:91], v[248:251], v[28:31], v[88:91]
	v_lshlrev_b32_e32 v92, 16, v154
	v_and_b32_e32 v93, 0xffff0000, v154
	v_lshlrev_b32_e32 v94, 16, v155
	v_and_b32_e32 v95, 0xffff0000, v155
	v_mul_f32_e32 v96, 0xbfb8aa3b, v92
	v_mul_f32_e32 v97, 0xbfb8aa3b, v93
	v_mul_f32_e32 v98, 0xbfb8aa3b, v94
	v_mul_f32_e32 v99, 0xbfb8aa3b, v95
	v_exp_f32_e32 v96, v96
	v_exp_f32_e32 v97, v97
	v_exp_f32_e32 v98, v98
	v_exp_f32_e32 v99, v99
	v_add_f32_e32 v96, 1.0, v96
	v_add_f32_e32 v97, 1.0, v97
	v_add_f32_e32 v98, 1.0, v98
	v_add_f32_e32 v99, 1.0, v99
	v_rcp_f32_e32 v96, v96
	v_rcp_f32_e32 v97, v97
	v_rcp_f32_e32 v98, v98
	v_rcp_f32_e32 v99, v99
	s_nop 0
	v_pk_mul_f32 v[96:97], v[96:97], v[92:93]
	v_pk_mul_f32 v[98:99], v[98:99], v[94:95]
	v_pk_fma_f32 v[84:85], v[84:85], v[2:3], v[88:89] op_sel_hi:[1,0,1]
	v_pk_fma_f32 v[86:87], v[86:87], v[2:3], v[90:91] op_sel_hi:[1,0,1]
	v_lshlrev_b32_e32 v88, 16, v168
	v_and_b32_e32 v89, 0xffff0000, v168
	v_lshlrev_b32_e32 v90, 16, v169
	v_and_b32_e32 v91, 0xffff0000, v169
	v_pk_fma_f32 v[84:85], s[76:77], v[88:89], v[84:85] op_sel_hi:[0,1,1]
	v_pk_fma_f32 v[86:87], s[76:77], v[90:91], v[86:87] op_sel_hi:[0,1,1]
	v_pk_mul_f32 v[84:85], v[96:97], v[84:85]
	v_pk_mul_f32 v[86:87], v[98:99], v[86:87]
	v_fmac_f32_e32 v176, v84, v84
	v_fmac_f32_e32 v176, v85, v85
	v_fmac_f32_e32 v176, v86, v86
	v_fmac_f32_e32 v176, v87, v87
	ds_read_b64_tr_b16 v[244:245], v179 offset:160
	ds_read_b64_tr_b16 v[246:247], v179 offset:1760
	ds_read_b64_tr_b16 v[248:249], v179 offset:12960
	ds_read_b64_tr_b16 v[250:251], v179 offset:14560
	ds_read_b64 v[168:169], v182 offset:160
	s_waitcnt lgkmcnt(5)
	v_mfma_f32_16x16x32_bf16 v[100:103], v[100:103], v[8:11], 0
	v_mfma_f32_16x16x32_bf16 v[100:103], v[108:111], v[12:15], v[100:103]
	v_mfma_f32_16x16x32_bf16 v[100:103], v[112:115], v[16:19], v[100:103]
	v_mfma_f32_16x16x32_bf16 v[100:103], v[116:119], v[20:23], v[100:103]
	v_mfma_f32_16x16x32_bf16 v[108:111], v[236:239], v[32:35], 0
	v_mfma_f32_16x16x32_bf16 v[108:111], v[240:243], v[104:107], v[108:111]
	v_lshlrev_b32_e32 v112, 16, v160
	v_and_b32_e32 v113, 0xffff0000, v160
	v_lshlrev_b32_e32 v114, 16, v161
	v_and_b32_e32 v115, 0xffff0000, v161
	v_mul_f32_e32 v116, 0xbfb8aa3b, v112
	v_mul_f32_e32 v117, 0xbfb8aa3b, v113
	v_mul_f32_e32 v118, 0xbfb8aa3b, v114
	v_mul_f32_e32 v119, 0xbfb8aa3b, v115
	v_exp_f32_e32 v116, v116
	v_exp_f32_e32 v117, v117
	v_exp_f32_e32 v118, v118
	v_exp_f32_e32 v119, v119
	v_add_f32_e32 v116, 1.0, v116
	v_add_f32_e32 v117, 1.0, v117
	v_add_f32_e32 v118, 1.0, v118
	v_add_f32_e32 v119, 1.0, v119
	v_rcp_f32_e32 v116, v116
	v_rcp_f32_e32 v117, v117
	v_rcp_f32_e32 v118, v118
	v_rcp_f32_e32 v119, v119
	s_nop 0
	v_pk_mul_f32 v[116:117], v[116:117], v[112:113]
	v_pk_mul_f32 v[118:119], v[118:119], v[114:115]
	v_pk_fma_f32 v[100:101], v[100:101], v[0:1], v[108:109] op_sel_hi:[1,0,1]
	v_pk_fma_f32 v[102:103], v[102:103], v[0:1], v[110:111] op_sel_hi:[1,0,1]
	v_lshlrev_b32_e32 v108, 16, v234
	v_and_b32_e32 v109, 0xffff0000, v234
	v_lshlrev_b32_e32 v110, 16, v235
	v_and_b32_e32 v111, 0xffff0000, v235
	v_pk_fma_f32 v[100:101], s[78:79], v[108:109], v[100:101] op_sel_hi:[0,1,1]
	v_pk_fma_f32 v[102:103], s[78:79], v[110:111], v[102:103] op_sel_hi:[0,1,1]
	v_pk_mul_f32 v[100:101], v[116:117], v[100:101]
	v_pk_mul_f32 v[102:103], v[118:119], v[102:103]
	v_fmac_f32_e32 v176, v100, v100
	v_fmac_f32_e32 v176, v101, v101
	v_fmac_f32_e32 v176, v102, v102
	v_fmac_f32_e32 v176, v103, v103
	s_waitcnt lgkmcnt(0)
; #define LAS __attribute__((address_space(3)))
; __device__ __forceinline__ float bflo(unsigned w) { return __uint_as_float(w << 16); }
; __device__ __forceinline__ float bfhi(unsigned w) { return __uint_as_float(w & 0xffff0000u); }
; __device__ __forceinline__ float siluf_(float x) { return x * __builtin_amdgcn_rcpf(1.0f + __expf(-x)); }
; #define MFMA16(a, b, c) __builtin_amdgcn_mfma_f32_16x16x32_bf16((a), (b), (c), 0, 0, 0)
; __device__ void m2_c_unit(LAS unsigned char* lds, KP& P_, int l, int bc, int grp) {
;     ...
;       for (int i = 0; i < 6; ++i) { const int pt = ph * 6 + i, hh = pt >> 2, head = grp * 3 + hh;
;           f32x4 ad = (f32x4){0.f, 0.f, 0.f, 0.f}, ao = (f32x4){0.f, 0.f, 0.f, 0.f};
;           bf16x8 hc[4];
; #pragma unroll
;           for (int ks = 0; ks < 4; ++ks) hc[ks] = hf[ks];
;           if (i < 5) { const int pn = pt + 1;
; #pragma unroll
;               for (int ks = 0; ks < 4; ++ks) hf[ks] = *(const bf16x8*)(stm + (((size_t)bc * 6 + grp * 3 + (pn >> 2)) * 64 + (pn & 3) * 16 + fr) * 128 + ks * 32 + fq * 8); }
; #pragma unroll
;           for (int ks = 0; ks < 2; ++ks) { const unsigned ta = xn_base + (unsigned)((32 * ks + 8 * fq + (fr >> 2)) * 400 + (16 * pt + 4 * (fr & 3)) * 2);
;               const bf16x8 a = tr_frag(ta, ta + 1600u), b = *(const LAS bf16x8*)(PH + hh * 4608 + tq * 72 + ks * 32 + fq * 8); ad = MFMA16(a, b, ad); }
; #pragma unroll
;           for (int ks = 0; ks < 4; ++ks) ao = MFMA16(hc[ks], cf[ks], ao);
;           const float ea = __expf(acs[hh * 64 + tq]), dsk = p.in[9][l * 6 + head]; const int pch = pt * 16 + fq * 4;
;           const float zv[4] = {bflo(zraw[i].x), bfhi(zraw[i].x), bflo(zraw[i].y), bfhi(zraw[i].y)};
;           f32x4 y;
;           const u32x2 xraw = *(const LAS u32x2*)(XN + tq * 200 + pch); const float xsv[4] = {bflo(xraw.x), bfhi(xraw.x), bflo(xraw.y), bfhi(xraw.y)};
; #pragma unroll
;           for (int j = 0; j < 4; ++j) { y[j] = (ad[j] + ea * ao[j] + dsk * xsv[j]) * siluf_(zv[j]); ssq += y[j] * y[j]; }
;           yv[i] = y; }
	v_mfma_f32_16x16x32_bf16 v[120:123], v[120:123], v[8:11], 0
	v_mfma_f32_16x16x32_bf16 v[120:123], v[124:127], v[12:15], v[120:123]
	v_mfma_f32_16x16x32_bf16 v[120:123], v[128:131], v[16:19], v[120:123]
	v_mfma_f32_16x16x32_bf16 v[120:123], v[132:135], v[20:23], v[120:123]
	v_mfma_f32_16x16x32_bf16 v[124:127], v[244:247], v[32:35], 0
	v_mfma_f32_16x16x32_bf16 v[124:127], v[248:251], v[104:107], v[124:127]
	v_lshlrev_b32_e32 v128, 16, v162
	v_and_b32_e32 v129, 0xffff0000, v162
	v_lshlrev_b32_e32 v130, 16, v163
	v_and_b32_e32 v131, 0xffff0000, v163
	v_mul_f32_e32 v132, 0xbfb8aa3b, v128
	v_mul_f32_e32 v133, 0xbfb8aa3b, v129
	v_mul_f32_e32 v134, 0xbfb8aa3b, v130
	v_mul_f32_e32 v135, 0xbfb8aa3b, v131
	v_exp_f32_e32 v132, v132
	v_exp_f32_e32 v133, v133
	v_exp_f32_e32 v134, v134
	v_exp_f32_e32 v135, v135
	v_add_f32_e32 v132, 1.0, v132
	v_add_f32_e32 v133, 1.0, v133
	v_add_f32_e32 v134, 1.0, v134
	v_add_f32_e32 v135, 1.0, v135
	v_rcp_f32_e32 v132, v132
	v_rcp_f32_e32 v133, v133
	v_rcp_f32_e32 v134, v134
	v_rcp_f32_e32 v135, v135
	s_nop 0
	v_pk_mul_f32 v[132:133], v[132:133], v[128:129]
	v_pk_mul_f32 v[134:135], v[134:135], v[130:131]
	v_pk_fma_f32 v[120:121], v[120:121], v[0:1], v[124:125] op_sel_hi:[1,0,1]
	v_pk_fma_f32 v[122:123], v[122:123], v[0:1], v[126:127] op_sel_hi:[1,0,1]
	v_lshlrev_b32_e32 v124, 16, v168
	v_and_b32_e32 v125, 0xffff0000, v168
	v_lshlrev_b32_e32 v126, 16, v169
	v_and_b32_e32 v127, 0xffff0000, v169
	v_pk_fma_f32 v[120:121], s[78:79], v[124:125], v[120:121] op_sel_hi:[0,1,1]
	v_pk_fma_f32 v[122:123], s[78:79], v[126:127], v[122:123] op_sel_hi:[0,1,1]
	v_pk_mul_f32 v[120:121], v[132:133], v[120:121]
	v_pk_mul_f32 v[122:123], v[134:135], v[122:123]
	v_fmac_f32_e32 v176, v120, v120
	v_fmac_f32_e32 v176, v121, v121
	v_fmac_f32_e32 v176, v122, v122
	v_fmac_f32_e32 v176, v123, v123
	s_branch .Lm2ct_join
.Lm2ct_ph1:
	ds_read_b128 v[24:27], v180 offset:9216
	ds_read_b128 v[28:31], v180 offset:9280
	ds_read_b128 v[32:35], v180 offset:18432
	ds_read_b128 v[104:107], v180 offset:18496
	ds_read_b32 v2, v192 offset:256
	ds_read_b32 v0, v192 offset:512
	ds_read_b64_tr_b16 v[236:237], v179 offset:192
	ds_read_b64_tr_b16 v[238:239], v179 offset:1792
	ds_read_b64_tr_b16 v[240:241], v179 offset:12992
	ds_read_b64_tr_b16 v[242:243], v179 offset:14592
	ds_read_b64 v[234:235], v182 offset:192
	s_waitcnt vmcnt(0) lgkmcnt(0)
	v_mul_f32_e32 v2, 0x3fb8aa3b, v2
	v_mul_f32_e32 v0, 0x3fb8aa3b, v0
	v_exp_f32_e32 v2, v2
	v_exp_f32_e32 v0, v0
	ds_read_b64_tr_b16 v[244:245], v179 offset:224
	ds_read_b64_tr_b16 v[246:247], v179 offset:1824
	ds_read_b64_tr_b16 v[248:249], v179 offset:13024
	ds_read_b64_tr_b16 v[250:251], v179 offset:14624
	ds_read_b64 v[168:169], v182 offset:224
	s_waitcnt lgkmcnt(5)
	v_mfma_f32_16x16x32_bf16 v[36:39], v[36:39], v[8:11], 0
	v_mfma_f32_16x16x32_bf16 v[36:39], v[40:43], v[12:15], v[36:39]
	v_mfma_f32_16x16x32_bf16 v[36:39], v[44:47], v[16:19], v[36:39]
	v_mfma_f32_16x16x32_bf16 v[36:39], v[48:51], v[20:23], v[36:39]
	v_mfma_f32_16x16x32_bf16 v[40:43], v[236:239], v[24:27], 0
	v_mfma_f32_16x16x32_bf16 v[40:43], v[240:243], v[28:31], v[40:43]
	v_lshlrev_b32_e32 v44, 16, v148
	v_and_b32_e32 v45, 0xffff0000, v148
	v_lshlrev_b32_e32 v46, 16, v149
	v_and_b32_e32 v47, 0xffff0000, v149
	v_mul_f32_e32 v48, 0xbfb8aa3b, v44
	v_mul_f32_e32 v49, 0xbfb8aa3b, v45
	v_mul_f32_e32 v50, 0xbfb8aa3b, v46
	v_mul_f32_e32 v51, 0xbfb8aa3b, v47
	v_exp_f32_e32 v48, v48
	v_exp_f32_e32 v49, v49
	v_exp_f32_e32 v50, v50
	v_exp_f32_e32 v51, v51
	v_add_f32_e32 v48, 1.0, v48
	v_add_f32_e32 v49, 1.0, v49
	v_add_f32_e32 v50, 1.0, v50
	v_add_f32_e32 v51, 1.0, v51
	v_rcp_f32_e32 v48, v48
	v_rcp_f32_e32 v49, v49
	v_rcp_f32_e32 v50, v50
	v_rcp_f32_e32 v51, v51
	s_nop 0
	v_pk_mul_f32 v[48:49], v[48:49], v[44:45]
	v_pk_mul_f32 v[50:51], v[50:51], v[46:47]
	v_pk_fma_f32 v[36:37], v[36:37], v[2:3], v[40:41] op_sel_hi:[1,0,1]
	v_pk_fma_f32 v[38:39], v[38:39], v[2:3], v[42:43] op_sel_hi:[1,0,1]
	v_lshlrev_b32_e32 v40, 16, v234
	v_and_b32_e32 v41, 0xffff0000, v234
	v_lshlrev_b32_e32 v42, 16, v235
	v_and_b32_e32 v43, 0xffff0000, v235
	v_pk_fma_f32 v[36:37], s[78:79], v[40:41], v[36:37] op_sel_hi:[0,1,1]
	v_pk_fma_f32 v[38:39], s[78:79], v[42:43], v[38:39] op_sel_hi:[0,1,1]
	v_pk_mul_f32 v[36:37], v[48:49], v[36:37]
	v_pk_mul_f32 v[38:39], v[50:51], v[38:39]
	v_fmac_f32_e32 v176, v36, v36
	v_fmac_f32_e32 v176, v37, v37
	v_fmac_f32_e32 v176, v38, v38
	v_fmac_f32_e32 v176, v39, v39
	ds_read_b64_tr_b16 v[236:237], v179 offset:256
	ds_read_b64_tr_b16 v[238:239], v179 offset:1856
	ds_read_b64_tr_b16 v[240:241], v179 offset:13056
	ds_read_b64_tr_b16 v[242:243], v179 offset:14656
	ds_read_b64 v[234:235], v182 offset:256
	s_waitcnt lgkmcnt(5)
; #define LAS __attribute__((address_space(3)))
; __device__ __forceinline__ float bflo(unsigned w) { return __uint_as_float(w << 16); }
; __device__ __forceinline__ float bfhi(unsigned w) { return __uint_as_float(w & 0xffff0000u); }
; __device__ __forceinline__ float siluf_(float x) { return x * __builtin_amdgcn_rcpf(1.0f + __expf(-x)); }
; #define MFMA16(a, b, c) __builtin_amdgcn_mfma_f32_16x16x32_bf16((a), (b), (c), 0, 0, 0)
; __device__ void m2_c_unit(LAS unsigned char* lds, KP& P_, int l, int bc, int grp) {
;     ...
;       for (int i = 0; i < 6; ++i) { const int pt = ph * 6 + i, hh = pt >> 2, head = grp * 3 + hh;
;           f32x4 ad = (f32x4){0.f, 0.f, 0.f, 0.f}, ao = (f32x4){0.f, 0.f, 0.f, 0.f};
;           bf16x8 hc[4];
; #pragma unroll
;           for (int ks = 0; ks < 4; ++ks) hc[ks] = hf[ks];
;           if (i < 5) { const int pn = pt + 1;
; #pragma unroll
;               for (int ks = 0; ks < 4; ++ks) hf[ks] = *(const bf16x8*)(stm + (((size_t)bc * 6 + grp * 3 + (pn >> 2)) * 64 + (pn & 3) * 16 + fr) * 128 + ks * 32 + fq * 8); }
; #pragma unroll
;           for (int ks = 0; ks < 2; ++ks) { const unsigned ta = xn_base + (unsigned)((32 * ks + 8 * fq + (fr >> 2)) * 400 + (16 * pt + 4 * (fr & 3)) * 2);
;               const bf16x8 a = tr_frag(ta, ta + 1600u), b = *(const LAS bf16x8*)(PH + hh * 4608 + tq * 72 + ks * 32 + fq * 8); ad = MFMA16(a, b, ad); }
; #pragma unroll
;           for (int ks = 0; ks < 4; ++ks) ao = MFMA16(hc[ks], cf[ks], ao);
;           const float ea = __expf(acs[hh * 64 + tq]), dsk = p.in[9][l * 6 + head]; const int pch = pt * 16 + fq * 4;
;           const float zv[4] = {bflo(zraw[i].x), bfhi(zraw[i].x), bflo(zraw[i].y), bfhi(zraw[i].y)};
;           f32x4 y;
;           const u32x2 xraw = *(const LAS u32x2*)(XN + tq * 200 + pch); const float xsv[4] = {bflo(xraw.x), bfhi(xraw.x), bflo(xraw.y), bfhi(xraw.y)};
; #pragma unroll
;           for (int j = 0; j < 4; ++j) { y[j] = (ad[j] + ea * ao[j] + dsk * xsv[j]) * siluf_(zv[j]); ssq += y[j] * y[j]; }
;           yv[i] = y; }
	v_mfma_f32_16x16x32_bf16 v[52:55], v[52:55], v[8:11], 0
	v_mfma_f32_16x16x32_bf16 v[52:55], v[56:59], v[12:15], v[52:55]
	v_mfma_f32_16x16x32_bf16 v[52:55], v[60:63], v[16:19], v[52:55]
	v_mfma_f32_16x16x32_bf16 v[52:55], v[64:67], v[20:23], v[52:55]
	v_mfma_f32_16x16x32_bf16 v[56:59], v[244:247], v[24:27], 0
	v_mfma_f32_16x16x32_bf16 v[56:59], v[248:251], v[28:31], v[56:59]
	v_lshlrev_b32_e32 v60, 16, v150
	v_and_b32_e32 v61, 0xffff0000, v150
	v_lshlrev_b32_e32 v62, 16, v151
	v_and_b32_e32 v63, 0xffff0000, v151
	v_mul_f32_e32 v64, 0xbfb8aa3b, v60
	v_mul_f32_e32 v65, 0xbfb8aa3b, v61
	v_mul_f32_e32 v66, 0xbfb8aa3b, v62
	v_mul_f32_e32 v67, 0xbfb8aa3b, v63
	v_exp_f32_e32 v64, v64
	v_exp_f32_e32 v65, v65
	v_exp_f32_e32 v66, v66
	v_exp_f32_e32 v67, v67
	v_add_f32_e32 v64, 1.0, v64
	v_add_f32_e32 v65, 1.0, v65
	v_add_f32_e32 v66, 1.0, v66
	v_add_f32_e32 v67, 1.0, v67
	v_rcp_f32_e32 v64, v64
	v_rcp_f32_e32 v65, v65
	v_rcp_f32_e32 v66, v66
	v_rcp_f32_e32 v67, v67
	s_nop 0
	v_pk_mul_f32 v[64:65], v[64:65], v[60:61]
	v_pk_mul_f32 v[66:67], v[66:67], v[62:63]
	v_pk_fma_f32 v[52:53], v[52:53], v[2:3], v[56:57] op_sel_hi:[1,0,1]
	v_pk_fma_f32 v[54:55], v[54:55], v[2:3], v[58:59] op_sel_hi:[1,0,1]
	v_lshlrev_b32_e32 v56, 16, v168
	v_and_b32_e32 v57, 0xffff0000, v168
	v_lshlrev_b32_e32 v58, 16, v169
	v_and_b32_e32 v59, 0xffff0000, v169
	v_pk_fma_f32 v[52:53], s[78:79], v[56:57], v[52:53] op_sel_hi:[0,1,1]
	v_pk_fma_f32 v[54:55], s[78:79], v[58:59], v[54:55] op_sel_hi:[0,1,1]
	v_pk_mul_f32 v[52:53], v[64:65], v[52:53]
	v_pk_mul_f32 v[54:55], v[66:67], v[54:55]
	v_fmac_f32_e32 v176, v52, v52
	v_fmac_f32_e32 v176, v53, v53
	v_fmac_f32_e32 v176, v54, v54
	v_fmac_f32_e32 v176, v55, v55
	ds_read_b64_tr_b16 v[244:245], v179 offset:288
	ds_read_b64_tr_b16 v[246:247], v179 offset:1888
	ds_read_b64_tr_b16 v[248:249], v179 offset:13088
	ds_read_b64_tr_b16 v[250:251], v179 offset:14688
	ds_read_b64 v[168:169], v182 offset:288
	s_waitcnt lgkmcnt(5)
	v_mfma_f32_16x16x32_bf16 v[68:71], v[68:71], v[8:11], 0
	v_mfma_f32_16x16x32_bf16 v[68:71], v[72:75], v[12:15], v[68:71]
	v_mfma_f32_16x16x32_bf16 v[68:71], v[76:79], v[16:19], v[68:71]
	v_mfma_f32_16x16x32_bf16 v[68:71], v[80:83], v[20:23], v[68:71]
	v_mfma_f32_16x16x32_bf16 v[72:75], v[236:239], v[32:35], 0
	v_mfma_f32_16x16x32_bf16 v[72:75], v[240:243], v[104:107], v[72:75]
	v_lshlrev_b32_e32 v76, 16, v152
	v_and_b32_e32 v77, 0xffff0000, v152
	v_lshlrev_b32_e32 v78, 16, v153
	v_and_b32_e32 v79, 0xffff0000, v153
	v_mul_f32_e32 v80, 0xbfb8aa3b, v76
	v_mul_f32_e32 v81, 0xbfb8aa3b, v77
	v_mul_f32_e32 v82, 0xbfb8aa3b, v78
	v_mul_f32_e32 v83, 0xbfb8aa3b, v79
	v_exp_f32_e32 v80, v80
	v_exp_f32_e32 v81, v81
	v_exp_f32_e32 v82, v82
	v_exp_f32_e32 v83, v83
	v_add_f32_e32 v80, 1.0, v80
	v_add_f32_e32 v81, 1.0, v81
	v_add_f32_e32 v82, 1.0, v82
	v_add_f32_e32 v83, 1.0, v83
	v_rcp_f32_e32 v80, v80
	v_rcp_f32_e32 v81, v81
	v_rcp_f32_e32 v82, v82
	v_rcp_f32_e32 v83, v83
	s_nop 0
	v_pk_mul_f32 v[80:81], v[80:81], v[76:77]
	v_pk_mul_f32 v[82:83], v[82:83], v[78:79]
	v_pk_fma_f32 v[68:69], v[68:69], v[0:1], v[72:73] op_sel_hi:[1,0,1]
	v_pk_fma_f32 v[70:71], v[70:71], v[0:1], v[74:75] op_sel_hi:[1,0,1]
	v_lshlrev_b32_e32 v72, 16, v234
	v_and_b32_e32 v73, 0xffff0000, v234
	v_lshlrev_b32_e32 v74, 16, v235
	v_and_b32_e32 v75, 0xffff0000, v235
	v_pk_fma_f32 v[68:69], s[70:71], v[72:73], v[68:69] op_sel_hi:[0,1,1]
	v_pk_fma_f32 v[70:71], s[70:71], v[74:75], v[70:71] op_sel_hi:[0,1,1]
	v_pk_mul_f32 v[68:69], v[80:81], v[68:69]
	v_pk_mul_f32 v[70:71], v[82:83], v[70:71]
	v_fmac_f32_e32 v176, v68, v68
	v_fmac_f32_e32 v176, v69, v69
	v_fmac_f32_e32 v176, v70, v70
	v_fmac_f32_e32 v176, v71, v71
	ds_read_b64_tr_b16 v[236:237], v179 offset:320
	ds_read_b64_tr_b16 v[238:239], v179 offset:1920
	ds_read_b64_tr_b16 v[240:241], v179 offset:13120
	ds_read_b64_tr_b16 v[242:243], v179 offset:14720
	ds_read_b64 v[234:235], v182 offset:320
	s_waitcnt lgkmcnt(5)
	v_mfma_f32_16x16x32_bf16 v[84:87], v[84:87], v[8:11], 0
	v_mfma_f32_16x16x32_bf16 v[84:87], v[88:91], v[12:15], v[84:87]
	v_mfma_f32_16x16x32_bf16 v[84:87], v[92:95], v[16:19], v[84:87]
	v_mfma_f32_16x16x32_bf16 v[84:87], v[96:99], v[20:23], v[84:87]
	v_mfma_f32_16x16x32_bf16 v[88:91], v[244:247], v[32:35], 0
	v_mfma_f32_16x16x32_bf16 v[88:91], v[248:251], v[104:107], v[88:91]
	v_lshlrev_b32_e32 v92, 16, v154
	v_and_b32_e32 v93, 0xffff0000, v154
	v_lshlrev_b32_e32 v94, 16, v155
	v_and_b32_e32 v95, 0xffff0000, v155
	v_mul_f32_e32 v96, 0xbfb8aa3b, v92
	v_mul_f32_e32 v97, 0xbfb8aa3b, v93
	v_mul_f32_e32 v98, 0xbfb8aa3b, v94
	v_mul_f32_e32 v99, 0xbfb8aa3b, v95
	v_exp_f32_e32 v96, v96
	v_exp_f32_e32 v97, v97
	v_exp_f32_e32 v98, v98
	v_exp_f32_e32 v99, v99
	v_add_f32_e32 v96, 1.0, v96
	v_add_f32_e32 v97, 1.0, v97
	v_add_f32_e32 v98, 1.0, v98
	v_add_f32_e32 v99, 1.0, v99
	v_rcp_f32_e32 v96, v96
	v_rcp_f32_e32 v97, v97
	v_rcp_f32_e32 v98, v98
	v_rcp_f32_e32 v99, v99
	s_nop 0
	v_pk_mul_f32 v[96:97], v[96:97], v[92:93]
	v_pk_mul_f32 v[98:99], v[98:99], v[94:95]
	v_pk_fma_f32 v[84:85], v[84:85], v[0:1], v[88:89] op_sel_hi:[1,0,1]
	v_pk_fma_f32 v[86:87], v[86:87], v[0:1], v[90:91] op_sel_hi:[1,0,1]
	v_lshlrev_b32_e32 v88, 16, v168
	v_and_b32_e32 v89, 0xffff0000, v168
	v_lshlrev_b32_e32 v90, 16, v169
	v_and_b32_e32 v91, 0xffff0000, v169
	v_pk_fma_f32 v[84:85], s[70:71], v[88:89], v[84:85] op_sel_hi:[0,1,1]
	v_pk_fma_f32 v[86:87], s[70:71], v[90:91], v[86:87] op_sel_hi:[0,1,1]
	v_pk_mul_f32 v[84:85], v[96:97], v[84:85]
	v_pk_mul_f32 v[86:87], v[98:99], v[86:87]
	v_fmac_f32_e32 v176, v84, v84
	v_fmac_f32_e32 v176, v85, v85
	v_fmac_f32_e32 v176, v86, v86
	v_fmac_f32_e32 v176, v87, v87
	ds_read_b64_tr_b16 v[244:245], v179 offset:352
	ds_read_b64_tr_b16 v[246:247], v179 offset:1952
	ds_read_b64_tr_b16 v[248:249], v179 offset:13152
	ds_read_b64_tr_b16 v[250:251], v179 offset:14752
	ds_read_b64 v[168:169], v182 offset:352
	s_waitcnt lgkmcnt(5)
; #define LAS __attribute__((address_space(3)))
; __device__ __forceinline__ float bflo(unsigned w) { return __uint_as_float(w << 16); }
; __device__ void m2_c_unit(LAS unsigned char* lds, KP& P_, int l, int bc, int grp) {
;     ...
;       for (int i = 0; i < 6; ++i) { const int pt = ph * 6 + i, hh = pt >> 2, head = grp * 3 + hh;
;           f32x4 ad = (f32x4){0.f, 0.f, 0.f, 0.f}, ao = (f32x4){0.f, 0.f, 0.f, 0.f};
;           bf16x8 hc[4];
; #pragma unroll
;           for (int ks = 0; ks < 4; ++ks) hc[ks] = hf[ks];
;           if (i < 5) { const int pn = pt + 1;
; #pragma unroll
;               for (int ks = 0; ks < 4; ++ks) hf[ks] = *(const bf16x8*)(stm + (((size_t)bc * 6 + grp * 3 + (pn >> 2)) * 64 + (pn & 3) * 16 + fr) * 128 + ks * 32 + fq * 8); }
; #pragma unroll
;           for (int ks = 0; ks < 2; ++ks) { const unsigned ta = xn_base + (unsigned)((32 * ks + 8 * fq + (fr >> 2)) * 400 + (16 * pt + 4 * (fr & 3)) * 2);
;               const bf16x8 a = tr_frag(ta, ta + 1600u), b = *(const LAS bf16x8*)(PH + hh * 4608 + tq * 72 + ks * 32 + fq * 8); ad = MFMA16(a, b, ad); }
; #pragma unroll
;           for (int ks = 0; ks < 4; ++ks) ao = MFMA16(hc[ks], cf[ks], ao);
;           const float ea = __expf(acs[hh * 64 + tq]), dsk = p.in[9][l * 6 + head]; const int pch = pt * 16 + fq * 4;
;           const float zv[4] = {bflo(zraw[i].x), bfhi(zraw[i].x), bflo(zraw[i].y), bfhi(zraw[i].y)};
;           f32x4 y;
;           const u32x2 xraw = *(const LAS u32x2*)(XN + tq * 200 + pch); const float xsv[4] = {bflo(xraw.x), bfhi(xraw.x), bflo(xraw.y), bfhi(xraw.y)};
; #pragma unroll
;           for (int j = 0; j < 4; ++j) { y[j] = (ad[j] + ea * ao[j] + dsk * xsv[j]) * siluf_(zv[j]); ssq += y[j] * y[j]; }
;           yv[i] = y; }
;       ssq += __shfl_xor(ssq, 16); ssq += __shfl_xor(ssq, 32);
;       if (fq == 0) ss[tq * 2 + ph] = ssq; }
;     LBAR();
;     { const float rinv = __builtin_amdgcn_rsqf((ss[tq * 2] + ss[tq * 2 + 1]) * (1.0f / 192.0f) + RMS_EPS);
;       bf16_t* mixed = (bf16_t*)(p.ws + WS_MIXED); const float* nw = p.in[10] + l * 384 + grp * 192;
; #pragma unroll
;       for (int i = 0; i < 6; ++i) { const int pch = (ph * 6 + i) * 16 + fq * 4; f32x4 r;
; #pragma unroll
;           for (int j = 0; j < 4; ++j) r[j] = yv[i][j] * rinv * nwv[i][j];
;           *(u32x2*)(mixed + orow * DM + 384 + grp * 192 + pch) = pack4(r); } }
	v_mfma_f32_16x16x32_bf16 v[100:103], v[100:103], v[8:11], 0
	v_mfma_f32_16x16x32_bf16 v[100:103], v[108:111], v[12:15], v[100:103]
	v_mfma_f32_16x16x32_bf16 v[100:103], v[112:115], v[16:19], v[100:103]
	v_mfma_f32_16x16x32_bf16 v[100:103], v[116:119], v[20:23], v[100:103]
	v_mfma_f32_16x16x32_bf16 v[108:111], v[236:239], v[32:35], 0
	v_mfma_f32_16x16x32_bf16 v[108:111], v[240:243], v[104:107], v[108:111]
	v_lshlrev_b32_e32 v112, 16, v160
	v_and_b32_e32 v113, 0xffff0000, v160
	v_lshlrev_b32_e32 v114, 16, v161
	v_and_b32_e32 v115, 0xffff0000, v161
	v_mul_f32_e32 v116, 0xbfb8aa3b, v112
	v_mul_f32_e32 v117, 0xbfb8aa3b, v113
	v_mul_f32_e32 v118, 0xbfb8aa3b, v114
	v_mul_f32_e32 v119, 0xbfb8aa3b, v115
	v_exp_f32_e32 v116, v116
	v_exp_f32_e32 v117, v117
	v_exp_f32_e32 v118, v118
	v_exp_f32_e32 v119, v119
	v_add_f32_e32 v116, 1.0, v116
	v_add_f32_e32 v117, 1.0, v117
	v_add_f32_e32 v118, 1.0, v118
	v_add_f32_e32 v119, 1.0, v119
	v_rcp_f32_e32 v116, v116
	v_rcp_f32_e32 v117, v117
	v_rcp_f32_e32 v118, v118
	v_rcp_f32_e32 v119, v119
	s_nop 0
	v_pk_mul_f32 v[116:117], v[116:117], v[112:113]
	v_pk_mul_f32 v[118:119], v[118:119], v[114:115]
	v_pk_fma_f32 v[100:101], v[100:101], v[0:1], v[108:109] op_sel_hi:[1,0,1]
	v_pk_fma_f32 v[102:103], v[102:103], v[0:1], v[110:111] op_sel_hi:[1,0,1]
	v_lshlrev_b32_e32 v108, 16, v234
	v_and_b32_e32 v109, 0xffff0000, v234
	v_lshlrev_b32_e32 v110, 16, v235
	v_and_b32_e32 v111, 0xffff0000, v235
	v_pk_fma_f32 v[100:101], s[70:71], v[108:109], v[100:101] op_sel_hi:[0,1,1]
	v_pk_fma_f32 v[102:103], s[70:71], v[110:111], v[102:103] op_sel_hi:[0,1,1]
	v_pk_mul_f32 v[100:101], v[116:117], v[100:101]
	v_pk_mul_f32 v[102:103], v[118:119], v[102:103]
	v_fmac_f32_e32 v176, v100, v100
	v_fmac_f32_e32 v176, v101, v101
	v_fmac_f32_e32 v176, v102, v102
	v_fmac_f32_e32 v176, v103, v103
	s_waitcnt lgkmcnt(0)
	v_mfma_f32_16x16x32_bf16 v[120:123], v[120:123], v[8:11], 0
	v_mfma_f32_16x16x32_bf16 v[120:123], v[124:127], v[12:15], v[120:123]
	v_mfma_f32_16x16x32_bf16 v[120:123], v[128:131], v[16:19], v[120:123]
	v_mfma_f32_16x16x32_bf16 v[120:123], v[132:135], v[20:23], v[120:123]
	v_mfma_f32_16x16x32_bf16 v[124:127], v[244:247], v[32:35], 0
	v_mfma_f32_16x16x32_bf16 v[124:127], v[248:251], v[104:107], v[124:127]
	v_lshlrev_b32_e32 v128, 16, v162
	v_and_b32_e32 v129, 0xffff0000, v162
	v_lshlrev_b32_e32 v130, 16, v163
	v_and_b32_e32 v131, 0xffff0000, v163
	v_mul_f32_e32 v132, 0xbfb8aa3b, v128
	v_mul_f32_e32 v133, 0xbfb8aa3b, v129
	v_mul_f32_e32 v134, 0xbfb8aa3b, v130
	v_mul_f32_e32 v135, 0xbfb8aa3b, v131
	v_exp_f32_e32 v132, v132
	v_exp_f32_e32 v133, v133
	v_exp_f32_e32 v134, v134
	v_exp_f32_e32 v135, v135
	v_add_f32_e32 v132, 1.0, v132
	v_add_f32_e32 v133, 1.0, v133
	v_add_f32_e32 v134, 1.0, v134
	v_add_f32_e32 v135, 1.0, v135
	v_rcp_f32_e32 v132, v132
	v_rcp_f32_e32 v133, v133
	v_rcp_f32_e32 v134, v134
	v_rcp_f32_e32 v135, v135
	s_nop 0
	v_pk_mul_f32 v[132:133], v[132:133], v[128:129]
	v_pk_mul_f32 v[134:135], v[134:135], v[130:131]
	v_pk_fma_f32 v[120:121], v[120:121], v[0:1], v[124:125] op_sel_hi:[1,0,1]
	v_pk_fma_f32 v[122:123], v[122:123], v[0:1], v[126:127] op_sel_hi:[1,0,1]
	v_lshlrev_b32_e32 v124, 16, v168
	v_and_b32_e32 v125, 0xffff0000, v168
	v_lshlrev_b32_e32 v126, 16, v169
	v_and_b32_e32 v127, 0xffff0000, v169
	v_pk_fma_f32 v[120:121], s[70:71], v[124:125], v[120:121] op_sel_hi:[0,1,1]
	v_pk_fma_f32 v[122:123], s[70:71], v[126:127], v[122:123] op_sel_hi:[0,1,1]
	v_pk_mul_f32 v[120:121], v[132:133], v[120:121]
	v_pk_mul_f32 v[122:123], v[134:135], v[122:123]
	v_fmac_f32_e32 v176, v120, v120
	v_fmac_f32_e32 v176, v121, v121
	v_fmac_f32_e32 v176, v122, v122
	v_fmac_f32_e32 v176, v123, v123
.Lm2ct_join:
	ds_bpermute_b32 v2, v170, v176
	s_waitcnt lgkmcnt(0)
	v_add_f32_e32 v176, v176, v2
	ds_bpermute_b32 v2, v172, v176
	s_waitcnt lgkmcnt(0)
	v_add_f32_e32 v176, v176, v2
	ds_write_b32 v194, v176
	s_waitcnt lgkmcnt(0)
	s_barrier
	v_lshlrev_b32_e32 v0, 3, v158
	v_add_u32_e32 v0, 0x16900, v0
	ds_read_b64 v[2:3], v0
	s_waitcnt lgkmcnt(0)
	v_add_f32_e32 v0, v2, v3
	v_fmamk_f32 v0, v0, 0x3baaaaab, v200
	v_rsq_f32_e32 v0, v0
	s_nop 0
	v_pk_mul_f32 v[36:37], v[36:37], v[0:1] op_sel_hi:[1,0]
	v_pk_mul_f32 v[38:39], v[38:39], v[0:1] op_sel_hi:[1,0]
	v_pk_mul_f32 v[36:37], v[164:165], v[36:37]
	v_pk_mul_f32 v[38:39], v[166:167], v[38:39]
	v_cvt_pk_bf16_f32 v36, v36, v37
	v_cvt_pk_bf16_f32 v37, v38, v39
	global_store_dwordx2 v[210:211], v[36:37], off
	v_pk_mul_f32 v[52:53], v[52:53], v[0:1] op_sel_hi:[1,0]
	v_pk_mul_f32 v[54:55], v[54:55], v[0:1] op_sel_hi:[1,0]
	v_pk_mul_f32 v[52:53], v[184:185], v[52:53]
	v_pk_mul_f32 v[54:55], v[186:187], v[54:55]
	v_cvt_pk_bf16_f32 v52, v52, v53
	v_cvt_pk_bf16_f32 v53, v54, v55
	global_store_dwordx2 v[210:211], v[52:53], off offset:32
	v_pk_mul_f32 v[68:69], v[68:69], v[0:1] op_sel_hi:[1,0]
	v_pk_mul_f32 v[70:71], v[70:71], v[0:1] op_sel_hi:[1,0]
	v_pk_mul_f32 v[68:69], v[188:189], v[68:69]
	v_pk_mul_f32 v[70:71], v[190:191], v[70:71]
	v_cvt_pk_bf16_f32 v68, v68, v69
	v_cvt_pk_bf16_f32 v69, v70, v71
	global_store_dwordx2 v[210:211], v[68:69], off offset:64
	v_pk_mul_f32 v[84:85], v[84:85], v[0:1] op_sel_hi:[1,0]
	v_pk_mul_f32 v[86:87], v[86:87], v[0:1] op_sel_hi:[1,0]
	v_pk_mul_f32 v[84:85], v[222:223], v[84:85]
	v_pk_mul_f32 v[86:87], v[224:225], v[86:87]
	v_cvt_pk_bf16_f32 v84, v84, v85
	v_cvt_pk_bf16_f32 v85, v86, v87
	global_store_dwordx2 v[210:211], v[84:85], off offset:96
	v_pk_mul_f32 v[100:101], v[100:101], v[0:1] op_sel_hi:[1,0]
	v_pk_mul_f32 v[102:103], v[102:103], v[0:1] op_sel_hi:[1,0]
	v_pk_mul_f32 v[100:101], v[226:227], v[100:101]
	v_pk_mul_f32 v[102:103], v[228:229], v[102:103]
	v_cvt_pk_bf16_f32 v100, v100, v101
	v_cvt_pk_bf16_f32 v101, v102, v103
	global_store_dwordx2 v[210:211], v[100:101], off offset:128
	v_pk_mul_f32 v[120:121], v[120:121], v[0:1] op_sel_hi:[1,0]
	v_pk_mul_f32 v[122:123], v[122:123], v[0:1] op_sel_hi:[1,0]
	v_pk_mul_f32 v[120:121], v[230:231], v[120:121]
	v_pk_mul_f32 v[122:123], v[232:233], v[122:123]
	v_cvt_pk_bf16_f32 v120, v120, v121
	v_cvt_pk_bf16_f32 v121, v122, v123
	global_store_dwordx2 v[210:211], v[120:121], off offset:160
	s_branch .Lm2ct_done
